# k=9 OpSwiglu epilogue: 16 dwordx2 stores per wave widened to 8 dwordx4 via v_permlane16_swap (same bytes, same addresses)
# baseline (speedup 1.0000x reference)
; __device__ __forceinline__ unsigned pkbf(float lo, float hi) { f32x2 v = {lo, hi}; bf16x2v b = __builtin_convertvector(v, bf16x2v); return __builtin_bit_cast(unsigned, b); }
; __device__ __forceinline__ float sigmoidf_(float x) { return 1.f / (1.f + __expf(-x)); }
;     __device__ __forceinline__ void operator()(int row, int col, f32x4 v0, f32x4 v1) const { *(u32x4*)(G + (size_t)row * 1024 + col) = pack8(v0, v1); }
;     __device__ __forceinline__ void operator()(const pg8::f32x4 (&acc)[2][2][4][2], const pg8::Unit& u, int wr, int wc, int fr, int fq) const {
;     ...
;         for (int ai = 0; ai < 2; ++ai)
; #pragma unroll
;             for (int m = 0; m < 4; ++m)
; #pragma unroll
;                 for (int bj = 0; bj < 2; ++bj) { op(row0 + ai * 128 + m * 16, col0 + bj * 128, acc[ai][bj][m][0], acc[ai][bj][m][1]); asm volatile("" ::: "memory"); }
;     __device__ __forceinline__ void operator()(int row, int col, f32x4 v0, f32x4 v1) const {
;         const float h0 = v0.x * sigmoidf_(v0.x) * v0.y, h1 = v0.z * sigmoidf_(v0.z) * v0.w, h2 = v1.x * sigmoidf_(v1.x) * v1.y, h3 = v1.z * sigmoidf_(v1.z) * v1.w;
;         u32x2 o; o.x = pkbf(h0, h1); o.y = pkbf(h2, h3);
;         *(u32x2*)(HID + (size_t)row * DFF + (col >> 1)) = o;
;     }
.LBB0_38:
	v_mbcnt_lo_u32_b32 v208, -1, 0
	v_mbcnt_hi_u32_b32 v208, -1, v208
	v_and_b32_e32 v208, 16, v208
	v_lshlrev_b32_e32 v206, 3, v208
	v_lshrrev_b32_e32 v208, 1, v208
	v_sub_u32_e32 v206, v206, v208
	v_mov_b32_e32 v207, 0
	v_mul_f32_e32 v146, 0xbfb8aa3b, v126
	v_mul_f32_e32 v147, 0xbfb8aa3b, v128
	v_exp_f32_e32 v146, v146
	v_exp_f32_e32 v147, v147
	v_lshl_or_b32 v145, s78, 8, v142
	v_lshl_add_u32 v144, s27, 8, v140
	v_pk_add_f32 v[146:147], v[146:147], 1.0 op_sel_hi:[1,0]
	s_nop 0
	v_rcp_f32_e32 v149, v147
	s_nop 0
	v_fma_f32 v150, -v147, v149, 1.0
	v_fmac_f32_e32 v149, v150, v149
	v_fma_f32 v152, -v147, v149, 1.0
	v_fma_f32 v151, v152, v149, v149
	v_fma_f32 v148, -v147, v151, 1.0
	v_fma_f32 v148, v148, v149, v151
	v_div_fixup_f32 v147, v148, v147, 1.0
	v_rcp_f32_e32 v149, v146
	s_nop 0
	v_fma_f32 v150, -v146, v149, 1.0
	v_fmac_f32_e32 v149, v150, v149
	v_fma_f32 v152, -v146, v149, 1.0
	v_fma_f32 v151, v152, v149, v149
	v_fma_f32 v148, -v146, v151, 1.0
	v_fma_f32 v148, v148, v149, v151
	v_div_fixup_f32 v146, v148, v146, 1.0
	v_mov_b32_e32 v148, v126
	v_mov_b32_e32 v149, v128
	v_pk_mul_f32 v[146:147], v[148:149], v[146:147]
	v_mov_b32_e32 v128, v127
	v_pk_mul_f32 v[126:127], v[128:129], v[146:147]
	v_mul_f32_e32 v128, 0xbfb8aa3b, v122
	v_mul_f32_e32 v129, 0xbfb8aa3b, v124
	v_exp_f32_e32 v128, v128
	v_exp_f32_e32 v129, v129
	v_cvt_pk_bf16_f32 v200, v126, v127
	v_pk_add_f32 v[128:129], v[128:129], 1.0 op_sel_hi:[1,0]
	s_nop 0
	v_rcp_f32_e32 v147, v129
	s_nop 0
	v_fma_f32 v148, -v129, v147, 1.0
	v_fmac_f32_e32 v147, v148, v147
	v_fma_f32 v150, -v129, v147, 1.0
	v_fma_f32 v149, v150, v147, v147
	v_fma_f32 v146, -v129, v149, 1.0
	v_fma_f32 v146, v146, v147, v149
	v_div_fixup_f32 v129, v146, v129, 1.0
	v_rcp_f32_e32 v147, v128
	s_nop 0
	v_fma_f32 v148, -v128, v147, 1.0
	v_fmac_f32_e32 v147, v148, v147
	v_fma_f32 v150, -v128, v147, 1.0
	v_fma_f32 v149, v150, v147, v147
	v_fma_f32 v146, -v128, v149, 1.0
	v_fma_f32 v146, v146, v147, v149
	v_div_fixup_f32 v128, v146, v128, 1.0
	v_mov_b32_e32 v146, v122
	v_mov_b32_e32 v147, v124
	v_pk_mul_f32 v[128:129], v[146:147], v[128:129]
	v_mov_b32_e32 v124, v123
	v_pk_mul_f32 v[122:123], v[124:125], v[128:129]
	v_ashrrev_i32_e32 v124, 1, v145
	v_cvt_pk_bf16_f32 v201, v122, v123
	v_mov_b64_e32 v[122:123], s[52:53]
	v_ashrrev_i32_e32 v125, 31, v124
	v_mad_i64_i32 v[128:129], s[4:5], v144, s86, v[122:123]
	v_lshlrev_b64 v[124:125], 1, v[124:125]
	v_lshl_add_u64 v[128:129], v[128:129], 0, v[124:125]
	v_mul_f32_e32 v126, 0xbfb8aa3b, v118
	v_mul_f32_e32 v127, 0xbfb8aa3b, v120
	v_exp_f32_e32 v126, v126
	v_exp_f32_e32 v127, v127
	s_nop 0
	v_pk_add_f32 v[126:127], v[126:127], 1.0 op_sel_hi:[1,0]
	s_nop 0
	v_rcp_f32_e32 v146, v127
	s_nop 0
	v_fma_f32 v147, -v127, v146, 1.0
	v_fmac_f32_e32 v146, v147, v146
	v_fma_f32 v149, -v127, v146, 1.0
	v_fma_f32 v148, v149, v146, v146
	v_fma_f32 v145, -v127, v148, 1.0
	v_fma_f32 v145, v145, v146, v148
	v_div_fixup_f32 v127, v145, v127, 1.0
	v_rcp_f32_e32 v146, v126
	s_nop 0
	v_fma_f32 v147, -v126, v146, 1.0
	v_fmac_f32_e32 v146, v147, v146
	v_fma_f32 v149, -v126, v146, 1.0
	v_fma_f32 v148, v149, v146, v146
	v_fma_f32 v145, -v126, v148, 1.0
	v_fma_f32 v145, v145, v146, v148
	v_div_fixup_f32 v126, v145, v126, 1.0
	v_mov_b32_e32 v146, v118
	v_mov_b32_e32 v147, v120
	v_pk_mul_f32 v[126:127], v[146:147], v[126:127]
	v_mov_b32_e32 v120, v119
	v_pk_mul_f32 v[118:119], v[120:121], v[126:127]
	v_mul_f32_e32 v120, 0xbfb8aa3b, v114
	v_mul_f32_e32 v121, 0xbfb8aa3b, v116
	v_exp_f32_e32 v120, v120
	v_exp_f32_e32 v121, v121
	s_nop 0
	v_pk_add_f32 v[120:121], v[120:121], 1.0 op_sel_hi:[1,0]
	s_nop 0
	v_rcp_f32_e32 v127, v121
	s_nop 0
	v_fma_f32 v145, -v121, v127, 1.0
	v_fmac_f32_e32 v127, v145, v127
	v_fma_f32 v147, -v121, v127, 1.0
	v_fma_f32 v146, v147, v127, v127
	v_fma_f32 v126, -v121, v146, 1.0
	v_fma_f32 v126, v126, v127, v146
	v_div_fixup_f32 v121, v126, v121, 1.0
	v_rcp_f32_e32 v127, v120
	s_nop 0
	v_fma_f32 v145, -v120, v127, 1.0
	v_fmac_f32_e32 v127, v145, v127
	v_fma_f32 v147, -v120, v127, 1.0
	v_fma_f32 v146, v147, v127, v127
	v_fma_f32 v126, -v120, v146, 1.0
	v_fma_f32 v126, v126, v127, v146
	v_div_fixup_f32 v120, v126, v120, 1.0
	v_mov_b32_e32 v126, v114
	v_mov_b32_e32 v127, v116
	v_pk_mul_f32 v[120:121], v[126:127], v[120:121]
	v_mov_b32_e32 v116, v115
	v_pk_mul_f32 v[114:115], v[116:117], v[120:121]
	v_cvt_pk_bf16_f32 v202, v118, v119
	v_cvt_pk_bf16_f32 v203, v114, v115
	v_mul_f32_e32 v114, 0xbfb8aa3b, v110
	v_mul_f32_e32 v115, 0xbfb8aa3b, v112
	v_exp_f32_e32 v114, v114
	v_exp_f32_e32 v115, v115
	s_nop 1
	v_permlane16_swap_b32 v200, v202
	v_permlane16_swap_b32 v201, v203
	v_lshl_add_u64 v[204:205], v[128:129], 0, v[206:207]
	global_store_dwordx4 v[204:205], v[200:203], off
	v_or_b32_e32 v118, 16, v144
	v_pk_add_f32 v[114:115], v[114:115], 1.0 op_sel_hi:[1,0]
	s_nop 0
	v_rcp_f32_e32 v117, v115
	s_nop 0
	v_fma_f32 v119, -v115, v117, 1.0
	v_fmac_f32_e32 v117, v119, v117
	v_fma_f32 v121, -v115, v117, 1.0
	v_fma_f32 v120, v121, v117, v117
	v_fma_f32 v116, -v115, v120, 1.0
	v_fma_f32 v116, v116, v117, v120
	v_div_fixup_f32 v115, v116, v115, 1.0
	v_rcp_f32_e32 v117, v114
	s_nop 0
	v_fma_f32 v119, -v114, v117, 1.0
	v_fmac_f32_e32 v117, v119, v117
	v_fma_f32 v121, -v114, v117, 1.0
	v_fma_f32 v120, v121, v117, v117
	v_fma_f32 v116, -v114, v120, 1.0
	v_fma_f32 v116, v116, v117, v120
	v_div_fixup_f32 v114, v116, v114, 1.0
	v_mov_b32_e32 v116, v110
	v_mov_b32_e32 v117, v112
	v_pk_mul_f32 v[114:115], v[116:117], v[114:115]
	v_mov_b32_e32 v112, v111
	v_pk_mul_f32 v[110:111], v[112:113], v[114:115]
	v_mul_f32_e32 v112, 0xbfb8aa3b, v106
	v_mul_f32_e32 v113, 0xbfb8aa3b, v108
	v_exp_f32_e32 v112, v112
; __device__ __forceinline__ unsigned pkbf(float lo, float hi) { f32x2 v = {lo, hi}; bf16x2v b = __builtin_convertvector(v, bf16x2v); return __builtin_bit_cast(unsigned, b); }
; __device__ __forceinline__ float sigmoidf_(float x) { return 1.f / (1.f + __expf(-x)); }
;     __device__ __forceinline__ void operator()(int row, int col, f32x4 v0, f32x4 v1) const { *(u32x4*)(G + (size_t)row * 1024 + col) = pack8(v0, v1); }
;     __device__ __forceinline__ void operator()(const pg8::f32x4 (&acc)[2][2][4][2], const pg8::Unit& u, int wr, int wc, int fr, int fq) const {
;     ...
;         for (int ai = 0; ai < 2; ++ai)
; #pragma unroll
;             for (int m = 0; m < 4; ++m)
; #pragma unroll
;                 for (int bj = 0; bj < 2; ++bj) { op(row0 + ai * 128 + m * 16, col0 + bj * 128, acc[ai][bj][m][0], acc[ai][bj][m][1]); asm volatile("" ::: "memory"); }
;     __device__ __forceinline__ void operator()(int row, int col, f32x4 v0, f32x4 v1) const {
;         const float h0 = v0.x * sigmoidf_(v0.x) * v0.y, h1 = v0.z * sigmoidf_(v0.z) * v0.w, h2 = v1.x * sigmoidf_(v1.x) * v1.y, h3 = v1.z * sigmoidf_(v1.z) * v1.w;
;         u32x2 o; o.x = pkbf(h0, h1); o.y = pkbf(h2, h3);
;         *(u32x2*)(HID + (size_t)row * DFF + (col >> 1)) = o;
;     }
	v_exp_f32_e32 v113, v113
	s_nop 0
	v_pk_add_f32 v[112:113], v[112:113], 1.0 op_sel_hi:[1,0]
	s_nop 0
	v_rcp_f32_e32 v115, v113
	s_nop 0
	v_fma_f32 v116, -v113, v115, 1.0
	v_fmac_f32_e32 v115, v116, v115
	v_fma_f32 v119, -v113, v115, 1.0
	v_fma_f32 v117, v119, v115, v115
	v_fma_f32 v114, -v113, v117, 1.0
	v_fma_f32 v114, v114, v115, v117
	v_div_fixup_f32 v113, v114, v113, 1.0
	v_rcp_f32_e32 v115, v112
	s_nop 0
	v_fma_f32 v116, -v112, v115, 1.0
	v_fmac_f32_e32 v115, v116, v115
	v_fma_f32 v119, -v112, v115, 1.0
	v_fma_f32 v117, v119, v115, v115
	v_fma_f32 v114, -v112, v117, 1.0
	v_fma_f32 v114, v114, v115, v117
	v_div_fixup_f32 v112, v114, v112, 1.0
	v_mov_b32_e32 v114, v106
	v_mov_b32_e32 v115, v108
	v_pk_mul_f32 v[112:113], v[114:115], v[112:113]
	v_mov_b32_e32 v108, v107
	v_pk_mul_f32 v[106:107], v[108:109], v[112:113]
	v_cvt_pk_bf16_f32 v200, v110, v111
	v_cvt_pk_bf16_f32 v201, v106, v107
	v_mad_i64_i32 v[106:107], s[4:5], v118, s86, v[122:123]
	v_lshl_add_u64 v[106:107], v[106:107], 0, v[124:125]
	v_mul_f32_e32 v108, 0xbfb8aa3b, v102
	v_mul_f32_e32 v109, 0xbfb8aa3b, v104
	v_exp_f32_e32 v108, v108
	v_exp_f32_e32 v109, v109
	s_nop 0
	v_pk_add_f32 v[108:109], v[108:109], 1.0 op_sel_hi:[1,0]
	s_nop 0
	v_rcp_f32_e32 v111, v109
	s_nop 0
	v_fma_f32 v112, -v109, v111, 1.0
	v_fmac_f32_e32 v111, v112, v111
	v_fma_f32 v114, -v109, v111, 1.0
	v_fma_f32 v113, v114, v111, v111
	v_fma_f32 v110, -v109, v113, 1.0
	v_fma_f32 v110, v110, v111, v113
	v_div_fixup_f32 v109, v110, v109, 1.0
	v_rcp_f32_e32 v111, v108
	s_nop 0
	v_fma_f32 v112, -v108, v111, 1.0
	v_fmac_f32_e32 v111, v112, v111
	v_fma_f32 v114, -v108, v111, 1.0
	v_fma_f32 v113, v114, v111, v111
	v_fma_f32 v110, -v108, v113, 1.0
	v_fma_f32 v110, v110, v111, v113
	v_div_fixup_f32 v108, v110, v108, 1.0
	v_mov_b32_e32 v110, v102
	v_mov_b32_e32 v111, v104
	v_pk_mul_f32 v[108:109], v[110:111], v[108:109]
	v_mov_b32_e32 v104, v103
	v_pk_mul_f32 v[102:103], v[104:105], v[108:109]
	v_mul_f32_e32 v104, 0xbfb8aa3b, v98
	v_mul_f32_e32 v105, 0xbfb8aa3b, v100
	v_exp_f32_e32 v104, v104
	v_exp_f32_e32 v105, v105
	s_nop 0
	v_pk_add_f32 v[104:105], v[104:105], 1.0 op_sel_hi:[1,0]
	s_nop 0
	v_rcp_f32_e32 v109, v105
	s_nop 0
	v_fma_f32 v110, -v105, v109, 1.0
	v_fmac_f32_e32 v109, v110, v109
	v_fma_f32 v112, -v105, v109, 1.0
	v_fma_f32 v111, v112, v109, v109
	v_fma_f32 v108, -v105, v111, 1.0
	v_fma_f32 v108, v108, v109, v111
	v_div_fixup_f32 v105, v108, v105, 1.0
	v_rcp_f32_e32 v109, v104
	s_nop 0
	v_fma_f32 v110, -v104, v109, 1.0
	v_fmac_f32_e32 v109, v110, v109
	v_fma_f32 v112, -v104, v109, 1.0
	v_fma_f32 v111, v112, v109, v109
	v_fma_f32 v108, -v104, v111, 1.0
	v_fma_f32 v108, v108, v109, v111
	v_div_fixup_f32 v104, v108, v104, 1.0
	v_mov_b32_e32 v108, v98
	v_mov_b32_e32 v109, v100
	v_pk_mul_f32 v[104:105], v[108:109], v[104:105]
	v_mov_b32_e32 v100, v99
	v_pk_mul_f32 v[98:99], v[100:101], v[104:105]
	v_cvt_pk_bf16_f32 v202, v102, v103
	v_cvt_pk_bf16_f32 v203, v98, v99
	v_mul_f32_e32 v98, 0xbfb8aa3b, v94
	v_mul_f32_e32 v99, 0xbfb8aa3b, v96
	v_exp_f32_e32 v98, v98
	v_exp_f32_e32 v99, v99
	s_nop 1
	v_permlane16_swap_b32 v200, v202
	v_permlane16_swap_b32 v201, v203
	v_lshl_add_u64 v[204:205], v[106:107], 0, v[206:207]
	global_store_dwordx4 v[204:205], v[200:203], off
	v_or_b32_e32 v102, 32, v144
	v_pk_add_f32 v[98:99], v[98:99], 1.0 op_sel_hi:[1,0]
	s_nop 0
	v_rcp_f32_e32 v101, v99
	s_nop 0
	v_fma_f32 v103, -v99, v101, 1.0
	v_fmac_f32_e32 v101, v103, v101
	v_fma_f32 v105, -v99, v101, 1.0
	v_fma_f32 v104, v105, v101, v101
	v_fma_f32 v100, -v99, v104, 1.0
	v_fma_f32 v100, v100, v101, v104
	v_div_fixup_f32 v99, v100, v99, 1.0
	v_rcp_f32_e32 v101, v98
	s_nop 0
	v_fma_f32 v103, -v98, v101, 1.0
	v_fmac_f32_e32 v101, v103, v101
	v_fma_f32 v105, -v98, v101, 1.0
	v_fma_f32 v104, v105, v101, v101
	v_fma_f32 v100, -v98, v104, 1.0
	v_fma_f32 v100, v100, v101, v104
	v_div_fixup_f32 v98, v100, v98, 1.0
	v_mov_b32_e32 v100, v94
	v_mov_b32_e32 v101, v96
	v_pk_mul_f32 v[98:99], v[100:101], v[98:99]
	v_mov_b32_e32 v96, v95
	v_pk_mul_f32 v[94:95], v[96:97], v[98:99]
	v_mul_f32_e32 v96, 0xbfb8aa3b, v90
	v_mul_f32_e32 v97, 0xbfb8aa3b, v92
	v_exp_f32_e32 v96, v96
	v_exp_f32_e32 v97, v97
	s_nop 0
	v_pk_add_f32 v[96:97], v[96:97], 1.0 op_sel_hi:[1,0]
	s_nop 0
	v_rcp_f32_e32 v99, v97
	s_nop 0
	v_fma_f32 v100, -v97, v99, 1.0
	v_fmac_f32_e32 v99, v100, v99
	v_fma_f32 v103, -v97, v99, 1.0
	v_fma_f32 v101, v103, v99, v99
	v_fma_f32 v98, -v97, v101, 1.0
	v_fma_f32 v98, v98, v99, v101
	v_div_fixup_f32 v97, v98, v97, 1.0
	v_rcp_f32_e32 v99, v96
	s_nop 0
	v_fma_f32 v100, -v96, v99, 1.0
	v_fmac_f32_e32 v99, v100, v99
	v_fma_f32 v103, -v96, v99, 1.0
	v_fma_f32 v101, v103, v99, v99
	v_fma_f32 v98, -v96, v101, 1.0
	v_fma_f32 v98, v98, v99, v101
	v_div_fixup_f32 v96, v98, v96, 1.0
	v_mov_b32_e32 v98, v90
	v_mov_b32_e32 v99, v92
	v_pk_mul_f32 v[96:97], v[98:99], v[96:97]
	v_mov_b32_e32 v92, v91
	v_pk_mul_f32 v[90:91], v[92:93], v[96:97]
	v_cvt_pk_bf16_f32 v200, v94, v95
	v_cvt_pk_bf16_f32 v201, v90, v91
	v_mad_i64_i32 v[90:91], s[4:5], v102, s86, v[122:123]
	v_lshl_add_u64 v[90:91], v[90:91], 0, v[124:125]
	v_mul_f32_e32 v92, 0xbfb8aa3b, v86
	v_mul_f32_e32 v93, 0xbfb8aa3b, v88
	v_exp_f32_e32 v92, v92
	v_exp_f32_e32 v93, v93
	s_nop 0
	v_pk_add_f32 v[92:93], v[92:93], 1.0 op_sel_hi:[1,0]
	s_nop 0
	v_rcp_f32_e32 v95, v93
	s_nop 0
	v_fma_f32 v96, -v93, v95, 1.0
	v_fmac_f32_e32 v95, v96, v95
	v_fma_f32 v98, -v93, v95, 1.0
	v_fma_f32 v97, v98, v95, v95
	v_fma_f32 v94, -v93, v97, 1.0
	v_fma_f32 v94, v94, v95, v97
	v_div_fixup_f32 v93, v94, v93, 1.0
	v_rcp_f32_e32 v95, v92
	s_nop 0
	v_fma_f32 v96, -v92, v95, 1.0
	v_fmac_f32_e32 v95, v96, v95
	v_fma_f32 v98, -v92, v95, 1.0
; __device__ __forceinline__ unsigned pkbf(float lo, float hi) { f32x2 v = {lo, hi}; bf16x2v b = __builtin_convertvector(v, bf16x2v); return __builtin_bit_cast(unsigned, b); }
; __device__ __forceinline__ float sigmoidf_(float x) { return 1.f / (1.f + __expf(-x)); }
;     __device__ __forceinline__ void operator()(int row, int col, f32x4 v0, f32x4 v1) const { *(u32x4*)(G + (size_t)row * 1024 + col) = pack8(v0, v1); }
;     __device__ __forceinline__ void operator()(const pg8::f32x4 (&acc)[2][2][4][2], const pg8::Unit& u, int wr, int wc, int fr, int fq) const {
;     ...
;         for (int ai = 0; ai < 2; ++ai)
; #pragma unroll
;             for (int m = 0; m < 4; ++m)
; #pragma unroll
;                 for (int bj = 0; bj < 2; ++bj) { op(row0 + ai * 128 + m * 16, col0 + bj * 128, acc[ai][bj][m][0], acc[ai][bj][m][1]); asm volatile("" ::: "memory"); }
;     __device__ __forceinline__ void operator()(int row, int col, f32x4 v0, f32x4 v1) const {
;         const float h0 = v0.x * sigmoidf_(v0.x) * v0.y, h1 = v0.z * sigmoidf_(v0.z) * v0.w, h2 = v1.x * sigmoidf_(v1.x) * v1.y, h3 = v1.z * sigmoidf_(v1.z) * v1.w;
;         u32x2 o; o.x = pkbf(h0, h1); o.y = pkbf(h2, h3);
;         *(u32x2*)(HID + (size_t)row * DFF + (col >> 1)) = o;
;     }
	v_fma_f32 v97, v98, v95, v95
	v_fma_f32 v94, -v92, v97, 1.0
	v_fma_f32 v94, v94, v95, v97
	v_div_fixup_f32 v92, v94, v92, 1.0
	v_mov_b32_e32 v94, v86
	v_mov_b32_e32 v95, v88
	v_pk_mul_f32 v[92:93], v[94:95], v[92:93]
	v_mov_b32_e32 v88, v87
	v_pk_mul_f32 v[86:87], v[88:89], v[92:93]
	v_mul_f32_e32 v88, 0xbfb8aa3b, v82
	v_mul_f32_e32 v89, 0xbfb8aa3b, v84
	v_exp_f32_e32 v88, v88
	v_exp_f32_e32 v89, v89
	s_nop 0
	v_pk_add_f32 v[88:89], v[88:89], 1.0 op_sel_hi:[1,0]
	s_nop 0
	v_rcp_f32_e32 v93, v89
	s_nop 0
	v_fma_f32 v94, -v89, v93, 1.0
	v_fmac_f32_e32 v93, v94, v93
	v_fma_f32 v96, -v89, v93, 1.0
	v_fma_f32 v95, v96, v93, v93
	v_fma_f32 v92, -v89, v95, 1.0
	v_fma_f32 v92, v92, v93, v95
	v_div_fixup_f32 v89, v92, v89, 1.0
	v_rcp_f32_e32 v93, v88
	s_nop 0
	v_fma_f32 v94, -v88, v93, 1.0
	v_fmac_f32_e32 v93, v94, v93
	v_fma_f32 v96, -v88, v93, 1.0
	v_fma_f32 v95, v96, v93, v93
	v_fma_f32 v92, -v88, v95, 1.0
	v_fma_f32 v92, v92, v93, v95
	v_div_fixup_f32 v88, v92, v88, 1.0
	v_mov_b32_e32 v92, v82
	v_mov_b32_e32 v93, v84
	v_pk_mul_f32 v[88:89], v[92:93], v[88:89]
	v_mov_b32_e32 v84, v83
	v_pk_mul_f32 v[82:83], v[84:85], v[88:89]
	v_cvt_pk_bf16_f32 v202, v86, v87
	v_cvt_pk_bf16_f32 v203, v82, v83
	v_mul_f32_e32 v82, 0xbfb8aa3b, v78
	v_mul_f32_e32 v83, 0xbfb8aa3b, v80
	v_exp_f32_e32 v82, v82
	v_exp_f32_e32 v83, v83
	s_nop 1
	v_permlane16_swap_b32 v200, v202
	v_permlane16_swap_b32 v201, v203
	v_lshl_add_u64 v[204:205], v[90:91], 0, v[206:207]
	global_store_dwordx4 v[204:205], v[200:203], off
	v_or_b32_e32 v86, 48, v144
	v_pk_add_f32 v[82:83], v[82:83], 1.0 op_sel_hi:[1,0]
	s_nop 0
	v_rcp_f32_e32 v85, v83
	s_nop 0
	v_fma_f32 v87, -v83, v85, 1.0
	v_fmac_f32_e32 v85, v87, v85
	v_fma_f32 v89, -v83, v85, 1.0
	v_fma_f32 v88, v89, v85, v85
	v_fma_f32 v84, -v83, v88, 1.0
	v_fma_f32 v84, v84, v85, v88
	v_div_fixup_f32 v83, v84, v83, 1.0
	v_rcp_f32_e32 v85, v82
	s_nop 0
	v_fma_f32 v87, -v82, v85, 1.0
	v_fmac_f32_e32 v85, v87, v85
	v_fma_f32 v89, -v82, v85, 1.0
	v_fma_f32 v88, v89, v85, v85
	v_fma_f32 v84, -v82, v88, 1.0
	v_fma_f32 v84, v84, v85, v88
	v_div_fixup_f32 v82, v84, v82, 1.0
	v_mov_b32_e32 v84, v78
	v_mov_b32_e32 v85, v80
	v_pk_mul_f32 v[82:83], v[84:85], v[82:83]
	v_mov_b32_e32 v80, v79
	v_pk_mul_f32 v[78:79], v[80:81], v[82:83]
	v_mul_f32_e32 v80, 0xbfb8aa3b, v74
	v_mul_f32_e32 v81, 0xbfb8aa3b, v76
	v_exp_f32_e32 v80, v80
	v_exp_f32_e32 v81, v81
	s_nop 0
	v_pk_add_f32 v[80:81], v[80:81], 1.0 op_sel_hi:[1,0]
	s_nop 0
	v_rcp_f32_e32 v83, v81
	s_nop 0
	v_fma_f32 v84, -v81, v83, 1.0
	v_fmac_f32_e32 v83, v84, v83
	v_fma_f32 v87, -v81, v83, 1.0
	v_fma_f32 v85, v87, v83, v83
	v_fma_f32 v82, -v81, v85, 1.0
	v_fma_f32 v82, v82, v83, v85
	v_div_fixup_f32 v81, v82, v81, 1.0
	v_rcp_f32_e32 v83, v80
	s_nop 0
	v_fma_f32 v84, -v80, v83, 1.0
	v_fmac_f32_e32 v83, v84, v83
	v_fma_f32 v87, -v80, v83, 1.0
	v_fma_f32 v85, v87, v83, v83
	v_fma_f32 v82, -v80, v85, 1.0
	v_fma_f32 v82, v82, v83, v85
	v_div_fixup_f32 v80, v82, v80, 1.0
	v_mov_b32_e32 v82, v74
	v_mov_b32_e32 v83, v76
	v_pk_mul_f32 v[80:81], v[82:83], v[80:81]
	v_mov_b32_e32 v76, v75
	v_pk_mul_f32 v[74:75], v[76:77], v[80:81]
	v_cvt_pk_bf16_f32 v200, v78, v79
	v_cvt_pk_bf16_f32 v201, v74, v75
	v_mad_i64_i32 v[74:75], s[4:5], v86, s86, v[122:123]
	v_lshl_add_u64 v[74:75], v[74:75], 0, v[124:125]
	v_mul_f32_e32 v76, 0xbfb8aa3b, v70
	v_mul_f32_e32 v77, 0xbfb8aa3b, v72
	v_exp_f32_e32 v76, v76
	v_exp_f32_e32 v77, v77
	s_nop 0
	v_pk_add_f32 v[76:77], v[76:77], 1.0 op_sel_hi:[1,0]
	s_nop 0
	v_rcp_f32_e32 v79, v77
	s_nop 0
	v_fma_f32 v80, -v77, v79, 1.0
	v_fmac_f32_e32 v79, v80, v79
	v_fma_f32 v82, -v77, v79, 1.0
	v_fma_f32 v81, v82, v79, v79
	v_fma_f32 v78, -v77, v81, 1.0
	v_fma_f32 v78, v78, v79, v81
	v_div_fixup_f32 v77, v78, v77, 1.0
	v_rcp_f32_e32 v79, v76
	s_nop 0
	v_fma_f32 v80, -v76, v79, 1.0
	v_fmac_f32_e32 v79, v80, v79
	v_fma_f32 v82, -v76, v79, 1.0
	v_fma_f32 v81, v82, v79, v79
	v_fma_f32 v78, -v76, v81, 1.0
	v_fma_f32 v78, v78, v79, v81
	v_div_fixup_f32 v76, v78, v76, 1.0
	v_mov_b32_e32 v78, v70
	v_mov_b32_e32 v79, v72
	v_pk_mul_f32 v[76:77], v[78:79], v[76:77]
	v_mov_b32_e32 v72, v71
	v_pk_mul_f32 v[70:71], v[72:73], v[76:77]
	v_mul_f32_e32 v72, 0xbfb8aa3b, v66
	v_mul_f32_e32 v73, 0xbfb8aa3b, v68
	v_exp_f32_e32 v72, v72
	v_exp_f32_e32 v73, v73
	s_nop 0
	v_pk_add_f32 v[72:73], v[72:73], 1.0 op_sel_hi:[1,0]
	s_nop 0
	v_rcp_f32_e32 v77, v73
	s_nop 0
	v_fma_f32 v78, -v73, v77, 1.0
	v_fmac_f32_e32 v77, v78, v77
	v_fma_f32 v80, -v73, v77, 1.0
	v_fma_f32 v79, v80, v77, v77
	v_fma_f32 v76, -v73, v79, 1.0
	v_fma_f32 v76, v76, v77, v79
	v_div_fixup_f32 v73, v76, v73, 1.0
	v_rcp_f32_e32 v77, v72
	s_nop 0
	v_fma_f32 v78, -v72, v77, 1.0
	v_fmac_f32_e32 v77, v78, v77
	v_fma_f32 v80, -v72, v77, 1.0
	v_fma_f32 v79, v80, v77, v77
	v_fma_f32 v76, -v72, v79, 1.0
	v_fma_f32 v76, v76, v77, v79
	v_div_fixup_f32 v72, v76, v72, 1.0
	v_mov_b32_e32 v76, v66
	v_mov_b32_e32 v77, v68
	v_pk_mul_f32 v[72:73], v[76:77], v[72:73]
	v_mov_b32_e32 v68, v67
	v_pk_mul_f32 v[66:67], v[68:69], v[72:73]
	v_cvt_pk_bf16_f32 v202, v70, v71
	v_cvt_pk_bf16_f32 v203, v66, v67
	v_mul_f32_e32 v66, 0xbfb8aa3b, v62
	v_mul_f32_e32 v67, 0xbfb8aa3b, v64
	v_exp_f32_e32 v66, v66
	v_exp_f32_e32 v67, v67
	s_nop 1
	v_permlane16_swap_b32 v200, v202
	v_permlane16_swap_b32 v201, v203
	v_lshl_add_u64 v[204:205], v[74:75], 0, v[206:207]
	global_store_dwordx4 v[204:205], v[200:203], off
	v_add_u32_e32 v70, 0x80, v144
	v_pk_add_f32 v[66:67], v[66:67], 1.0 op_sel_hi:[1,0]
	s_nop 0
	v_rcp_f32_e32 v69, v67
	s_nop 0
	v_fma_f32 v71, -v67, v69, 1.0
	v_fmac_f32_e32 v69, v71, v69
	v_fma_f32 v73, -v67, v69, 1.0
	v_fma_f32 v72, v73, v69, v69
	v_fma_f32 v68, -v67, v72, 1.0
; __device__ __forceinline__ unsigned pkbf(float lo, float hi) { f32x2 v = {lo, hi}; bf16x2v b = __builtin_convertvector(v, bf16x2v); return __builtin_bit_cast(unsigned, b); }
; __device__ __forceinline__ float sigmoidf_(float x) { return 1.f / (1.f + __expf(-x)); }
;     __device__ __forceinline__ void operator()(int row, int col, f32x4 v0, f32x4 v1) const { *(u32x4*)(G + (size_t)row * 1024 + col) = pack8(v0, v1); }
;     __device__ __forceinline__ void operator()(const pg8::f32x4 (&acc)[2][2][4][2], const pg8::Unit& u, int wr, int wc, int fr, int fq) const {
;     ...
;         for (int ai = 0; ai < 2; ++ai)
; #pragma unroll
;             for (int m = 0; m < 4; ++m)
; #pragma unroll
;                 for (int bj = 0; bj < 2; ++bj) { op(row0 + ai * 128 + m * 16, col0 + bj * 128, acc[ai][bj][m][0], acc[ai][bj][m][1]); asm volatile("" ::: "memory"); }
;     __device__ __forceinline__ void operator()(int row, int col, f32x4 v0, f32x4 v1) const {
;         const float h0 = v0.x * sigmoidf_(v0.x) * v0.y, h1 = v0.z * sigmoidf_(v0.z) * v0.w, h2 = v1.x * sigmoidf_(v1.x) * v1.y, h3 = v1.z * sigmoidf_(v1.z) * v1.w;
;         u32x2 o; o.x = pkbf(h0, h1); o.y = pkbf(h2, h3);
;         *(u32x2*)(HID + (size_t)row * DFF + (col >> 1)) = o;
;     }
	v_fma_f32 v68, v68, v69, v72
	v_div_fixup_f32 v67, v68, v67, 1.0
	v_rcp_f32_e32 v69, v66
	s_nop 0
	v_fma_f32 v71, -v66, v69, 1.0
	v_fmac_f32_e32 v69, v71, v69
	v_fma_f32 v73, -v66, v69, 1.0
	v_fma_f32 v72, v73, v69, v69
	v_fma_f32 v68, -v66, v72, 1.0
	v_fma_f32 v68, v68, v69, v72
	v_div_fixup_f32 v66, v68, v66, 1.0
	v_mov_b32_e32 v68, v62
	v_mov_b32_e32 v69, v64
	v_pk_mul_f32 v[66:67], v[68:69], v[66:67]
	v_mov_b32_e32 v64, v63
	v_pk_mul_f32 v[62:63], v[64:65], v[66:67]
	v_mul_f32_e32 v64, 0xbfb8aa3b, v58
	v_mul_f32_e32 v65, 0xbfb8aa3b, v60
	v_exp_f32_e32 v64, v64
	v_exp_f32_e32 v65, v65
	s_nop 0
	v_pk_add_f32 v[64:65], v[64:65], 1.0 op_sel_hi:[1,0]
	s_nop 0
	v_rcp_f32_e32 v67, v65
	s_nop 0
	v_fma_f32 v68, -v65, v67, 1.0
	v_fmac_f32_e32 v67, v68, v67
	v_fma_f32 v71, -v65, v67, 1.0
	v_fma_f32 v69, v71, v67, v67
	v_fma_f32 v66, -v65, v69, 1.0
	v_fma_f32 v66, v66, v67, v69
	v_div_fixup_f32 v65, v66, v65, 1.0
	v_rcp_f32_e32 v67, v64
	s_nop 0
	v_fma_f32 v68, -v64, v67, 1.0
	v_fmac_f32_e32 v67, v68, v67
	v_fma_f32 v71, -v64, v67, 1.0
	v_fma_f32 v69, v71, v67, v67
	v_fma_f32 v66, -v64, v69, 1.0
	v_fma_f32 v66, v66, v67, v69
	v_div_fixup_f32 v64, v66, v64, 1.0
	v_mov_b32_e32 v66, v58
	v_mov_b32_e32 v67, v60
	v_pk_mul_f32 v[64:65], v[66:67], v[64:65]
	v_mov_b32_e32 v60, v59
	v_pk_mul_f32 v[58:59], v[60:61], v[64:65]
	v_cvt_pk_bf16_f32 v200, v62, v63
	v_cvt_pk_bf16_f32 v201, v58, v59
	v_mad_i64_i32 v[58:59], s[4:5], v70, s86, v[122:123]
	v_lshl_add_u64 v[58:59], v[58:59], 0, v[124:125]
	v_mul_f32_e32 v60, 0xbfb8aa3b, v54
	v_mul_f32_e32 v61, 0xbfb8aa3b, v56
	v_exp_f32_e32 v60, v60
	v_exp_f32_e32 v61, v61
	s_nop 0
	v_pk_add_f32 v[60:61], v[60:61], 1.0 op_sel_hi:[1,0]
	s_nop 0
	v_rcp_f32_e32 v63, v61
	s_nop 0
	v_fma_f32 v64, -v61, v63, 1.0
	v_fmac_f32_e32 v63, v64, v63
	v_fma_f32 v66, -v61, v63, 1.0
	v_fma_f32 v65, v66, v63, v63
	v_fma_f32 v62, -v61, v65, 1.0
	v_fma_f32 v62, v62, v63, v65
	v_div_fixup_f32 v61, v62, v61, 1.0
	v_rcp_f32_e32 v63, v60
	s_nop 0
	v_fma_f32 v64, -v60, v63, 1.0
	v_fmac_f32_e32 v63, v64, v63
	v_fma_f32 v66, -v60, v63, 1.0
	v_fma_f32 v65, v66, v63, v63
	v_fma_f32 v62, -v60, v65, 1.0
	v_fma_f32 v62, v62, v63, v65
	v_div_fixup_f32 v60, v62, v60, 1.0
	v_mov_b32_e32 v62, v54
	v_mov_b32_e32 v63, v56
	v_pk_mul_f32 v[60:61], v[62:63], v[60:61]
	v_mov_b32_e32 v56, v55
	v_pk_mul_f32 v[54:55], v[56:57], v[60:61]
	v_mul_f32_e32 v56, 0xbfb8aa3b, v50
	v_mul_f32_e32 v57, 0xbfb8aa3b, v52
	v_exp_f32_e32 v56, v56
	v_exp_f32_e32 v57, v57
	s_nop 0
	v_pk_add_f32 v[56:57], v[56:57], 1.0 op_sel_hi:[1,0]
	s_nop 0
	v_rcp_f32_e32 v61, v57
	s_nop 0
	v_fma_f32 v62, -v57, v61, 1.0
	v_fmac_f32_e32 v61, v62, v61
	v_fma_f32 v64, -v57, v61, 1.0
	v_fma_f32 v63, v64, v61, v61
	v_fma_f32 v60, -v57, v63, 1.0
	v_fma_f32 v60, v60, v61, v63
	v_div_fixup_f32 v57, v60, v57, 1.0
	v_rcp_f32_e32 v61, v56
	s_nop 0
	v_fma_f32 v62, -v56, v61, 1.0
	v_fmac_f32_e32 v61, v62, v61
	v_fma_f32 v64, -v56, v61, 1.0
	v_fma_f32 v63, v64, v61, v61
	v_fma_f32 v60, -v56, v63, 1.0
	v_fma_f32 v60, v60, v61, v63
	v_div_fixup_f32 v56, v60, v56, 1.0
	v_mov_b32_e32 v60, v50
	v_mov_b32_e32 v61, v52
	v_pk_mul_f32 v[56:57], v[60:61], v[56:57]
	v_mov_b32_e32 v52, v51
	v_pk_mul_f32 v[50:51], v[52:53], v[56:57]
	v_cvt_pk_bf16_f32 v202, v54, v55
	v_cvt_pk_bf16_f32 v203, v50, v51
	v_mul_f32_e32 v50, 0xbfb8aa3b, v46
	v_mul_f32_e32 v51, 0xbfb8aa3b, v48
	v_exp_f32_e32 v50, v50
	v_exp_f32_e32 v51, v51
	s_nop 1
	v_permlane16_swap_b32 v200, v202
	v_permlane16_swap_b32 v201, v203
	v_lshl_add_u64 v[204:205], v[58:59], 0, v[206:207]
	global_store_dwordx4 v[204:205], v[200:203], off
	v_add_u32_e32 v54, 0x90, v144
	v_pk_add_f32 v[50:51], v[50:51], 1.0 op_sel_hi:[1,0]
	s_nop 0
	v_rcp_f32_e32 v53, v51
	s_nop 0
	v_fma_f32 v55, -v51, v53, 1.0
	v_fmac_f32_e32 v53, v55, v53
	v_fma_f32 v57, -v51, v53, 1.0
	v_fma_f32 v56, v57, v53, v53
	v_fma_f32 v52, -v51, v56, 1.0
	v_fma_f32 v52, v52, v53, v56
	v_div_fixup_f32 v51, v52, v51, 1.0
	v_rcp_f32_e32 v53, v50
	s_nop 0
	v_fma_f32 v55, -v50, v53, 1.0
	v_fmac_f32_e32 v53, v55, v53
	v_fma_f32 v57, -v50, v53, 1.0
	v_fma_f32 v56, v57, v53, v53
	v_fma_f32 v52, -v50, v56, 1.0
	v_fma_f32 v52, v52, v53, v56
	v_div_fixup_f32 v50, v52, v50, 1.0
	v_mov_b32_e32 v52, v46
	v_mov_b32_e32 v53, v48
	v_pk_mul_f32 v[50:51], v[52:53], v[50:51]
	v_mov_b32_e32 v48, v47
	v_pk_mul_f32 v[46:47], v[48:49], v[50:51]
	v_mul_f32_e32 v48, 0xbfb8aa3b, v42
	v_mul_f32_e32 v49, 0xbfb8aa3b, v44
	v_exp_f32_e32 v48, v48
	v_exp_f32_e32 v49, v49
	s_nop 0
	v_pk_add_f32 v[48:49], v[48:49], 1.0 op_sel_hi:[1,0]
	s_nop 0
	v_rcp_f32_e32 v51, v49
	s_nop 0
	v_fma_f32 v52, -v49, v51, 1.0
	v_fmac_f32_e32 v51, v52, v51
	v_fma_f32 v55, -v49, v51, 1.0
	v_fma_f32 v53, v55, v51, v51
	v_fma_f32 v50, -v49, v53, 1.0
	v_fma_f32 v50, v50, v51, v53
	v_div_fixup_f32 v49, v50, v49, 1.0
	v_rcp_f32_e32 v51, v48
	s_nop 0
	v_fma_f32 v52, -v48, v51, 1.0
	v_fmac_f32_e32 v51, v52, v51
	v_fma_f32 v55, -v48, v51, 1.0
	v_fma_f32 v53, v55, v51, v51
	v_fma_f32 v50, -v48, v53, 1.0
	v_fma_f32 v50, v50, v51, v53
	v_div_fixup_f32 v48, v50, v48, 1.0
	v_mov_b32_e32 v50, v42
	v_mov_b32_e32 v51, v44
	v_pk_mul_f32 v[48:49], v[50:51], v[48:49]
	v_mov_b32_e32 v44, v43
	v_pk_mul_f32 v[42:43], v[44:45], v[48:49]
	v_cvt_pk_bf16_f32 v200, v46, v47
	v_cvt_pk_bf16_f32 v201, v42, v43
	v_mad_i64_i32 v[42:43], s[4:5], v54, s86, v[122:123]
	v_lshl_add_u64 v[42:43], v[42:43], 0, v[124:125]
	v_mul_f32_e32 v44, 0xbfb8aa3b, v38
	v_mul_f32_e32 v45, 0xbfb8aa3b, v40
	v_exp_f32_e32 v44, v44
	v_exp_f32_e32 v45, v45
	s_nop 0
	v_pk_add_f32 v[44:45], v[44:45], 1.0 op_sel_hi:[1,0]
	s_nop 0
	v_rcp_f32_e32 v47, v45
	s_nop 0
	v_fma_f32 v48, -v45, v47, 1.0
	v_fmac_f32_e32 v47, v48, v47
; __device__ __forceinline__ unsigned pkbf(float lo, float hi) { f32x2 v = {lo, hi}; bf16x2v b = __builtin_convertvector(v, bf16x2v); return __builtin_bit_cast(unsigned, b); }
; __device__ __forceinline__ float sigmoidf_(float x) { return 1.f / (1.f + __expf(-x)); }
;     __device__ __forceinline__ void operator()(int row, int col, f32x4 v0, f32x4 v1) const { *(u32x4*)(G + (size_t)row * 1024 + col) = pack8(v0, v1); }
;     __device__ __forceinline__ void operator()(const pg8::f32x4 (&acc)[2][2][4][2], const pg8::Unit& u, int wr, int wc, int fr, int fq) const {
;     ...
;         for (int ai = 0; ai < 2; ++ai)
; #pragma unroll
;             for (int m = 0; m < 4; ++m)
; #pragma unroll
;                 for (int bj = 0; bj < 2; ++bj) { op(row0 + ai * 128 + m * 16, col0 + bj * 128, acc[ai][bj][m][0], acc[ai][bj][m][1]); asm volatile("" ::: "memory"); }
;     __device__ __forceinline__ void operator()(int row, int col, f32x4 v0, f32x4 v1) const {
;         const float h0 = v0.x * sigmoidf_(v0.x) * v0.y, h1 = v0.z * sigmoidf_(v0.z) * v0.w, h2 = v1.x * sigmoidf_(v1.x) * v1.y, h3 = v1.z * sigmoidf_(v1.z) * v1.w;
;         u32x2 o; o.x = pkbf(h0, h1); o.y = pkbf(h2, h3);
;         *(u32x2*)(HID + (size_t)row * DFF + (col >> 1)) = o;
;     }
	v_fma_f32 v50, -v45, v47, 1.0
	v_fma_f32 v49, v50, v47, v47
	v_fma_f32 v46, -v45, v49, 1.0
	v_fma_f32 v46, v46, v47, v49
	v_div_fixup_f32 v45, v46, v45, 1.0
	v_rcp_f32_e32 v47, v44
	s_nop 0
	v_fma_f32 v48, -v44, v47, 1.0
	v_fmac_f32_e32 v47, v48, v47
	v_fma_f32 v50, -v44, v47, 1.0
	v_fma_f32 v49, v50, v47, v47
	v_fma_f32 v46, -v44, v49, 1.0
	v_fma_f32 v46, v46, v47, v49
	v_div_fixup_f32 v44, v46, v44, 1.0
	v_mov_b32_e32 v46, v38
	v_mov_b32_e32 v47, v40
	v_pk_mul_f32 v[44:45], v[46:47], v[44:45]
	v_mov_b32_e32 v40, v39
	v_pk_mul_f32 v[38:39], v[40:41], v[44:45]
	v_mul_f32_e32 v40, 0xbfb8aa3b, v34
	v_mul_f32_e32 v41, 0xbfb8aa3b, v36
	v_exp_f32_e32 v40, v40
	v_exp_f32_e32 v41, v41
	s_nop 0
	v_pk_add_f32 v[40:41], v[40:41], 1.0 op_sel_hi:[1,0]
	s_nop 0
	v_rcp_f32_e32 v45, v41
	s_nop 0
	v_fma_f32 v46, -v41, v45, 1.0
	v_fmac_f32_e32 v45, v46, v45
	v_fma_f32 v48, -v41, v45, 1.0
	v_fma_f32 v47, v48, v45, v45
	v_fma_f32 v44, -v41, v47, 1.0
	v_fma_f32 v44, v44, v45, v47
	v_div_fixup_f32 v41, v44, v41, 1.0
	v_rcp_f32_e32 v45, v40
	s_nop 0
	v_fma_f32 v46, -v40, v45, 1.0
	v_fmac_f32_e32 v45, v46, v45
	v_fma_f32 v48, -v40, v45, 1.0
	v_fma_f32 v47, v48, v45, v45
	v_fma_f32 v44, -v40, v47, 1.0
	v_fma_f32 v44, v44, v45, v47
	v_div_fixup_f32 v40, v44, v40, 1.0
	v_mov_b32_e32 v44, v34
	v_mov_b32_e32 v45, v36
	v_pk_mul_f32 v[40:41], v[44:45], v[40:41]
	v_mov_b32_e32 v36, v35
	v_pk_mul_f32 v[34:35], v[36:37], v[40:41]
	v_cvt_pk_bf16_f32 v202, v38, v39
	v_cvt_pk_bf16_f32 v203, v34, v35
	v_mul_f32_e32 v34, 0xbfb8aa3b, v30
	v_mul_f32_e32 v35, 0xbfb8aa3b, v32
	v_exp_f32_e32 v34, v34
	v_exp_f32_e32 v35, v35
	s_nop 1
	v_permlane16_swap_b32 v200, v202
	v_permlane16_swap_b32 v201, v203
	v_lshl_add_u64 v[204:205], v[42:43], 0, v[206:207]
	global_store_dwordx4 v[204:205], v[200:203], off
	v_add_u32_e32 v38, 0xa0, v144
	v_pk_add_f32 v[34:35], v[34:35], 1.0 op_sel_hi:[1,0]
	s_nop 0
	v_rcp_f32_e32 v37, v35
	s_nop 0
	v_fma_f32 v39, -v35, v37, 1.0
	v_fmac_f32_e32 v37, v39, v37
	v_fma_f32 v41, -v35, v37, 1.0
	v_fma_f32 v40, v41, v37, v37
	v_fma_f32 v36, -v35, v40, 1.0
	v_fma_f32 v36, v36, v37, v40
	v_div_fixup_f32 v35, v36, v35, 1.0
	v_rcp_f32_e32 v37, v34
	s_nop 0
	v_fma_f32 v39, -v34, v37, 1.0
	v_fmac_f32_e32 v37, v39, v37
	v_fma_f32 v41, -v34, v37, 1.0
	v_fma_f32 v40, v41, v37, v37
	v_fma_f32 v36, -v34, v40, 1.0
	v_fma_f32 v36, v36, v37, v40
	v_div_fixup_f32 v34, v36, v34, 1.0
	v_mov_b32_e32 v36, v30
	v_mov_b32_e32 v37, v32
	v_pk_mul_f32 v[34:35], v[36:37], v[34:35]
	v_mov_b32_e32 v32, v31
	v_pk_mul_f32 v[30:31], v[32:33], v[34:35]
	v_mul_f32_e32 v32, 0xbfb8aa3b, v26
	v_mul_f32_e32 v33, 0xbfb8aa3b, v28
	v_exp_f32_e32 v32, v32
	v_exp_f32_e32 v33, v33
	s_nop 0
	v_pk_add_f32 v[32:33], v[32:33], 1.0 op_sel_hi:[1,0]
	s_nop 0
	v_rcp_f32_e32 v35, v33
	s_nop 0
	v_fma_f32 v36, -v33, v35, 1.0
	v_fmac_f32_e32 v35, v36, v35
	v_fma_f32 v39, -v33, v35, 1.0
	v_fma_f32 v37, v39, v35, v35
	v_fma_f32 v34, -v33, v37, 1.0
	v_fma_f32 v34, v34, v35, v37
	v_div_fixup_f32 v33, v34, v33, 1.0
	v_rcp_f32_e32 v35, v32
	s_nop 0
	v_fma_f32 v36, -v32, v35, 1.0
	v_fmac_f32_e32 v35, v36, v35
	v_fma_f32 v39, -v32, v35, 1.0
	v_fma_f32 v37, v39, v35, v35
	v_fma_f32 v34, -v32, v37, 1.0
	v_fma_f32 v34, v34, v35, v37
	v_div_fixup_f32 v32, v34, v32, 1.0
	v_mov_b32_e32 v34, v26
	v_mov_b32_e32 v35, v28
	v_pk_mul_f32 v[32:33], v[34:35], v[32:33]
	v_mov_b32_e32 v28, v27
	v_pk_mul_f32 v[26:27], v[28:29], v[32:33]
	v_cvt_pk_bf16_f32 v200, v30, v31
	v_cvt_pk_bf16_f32 v201, v26, v27
	v_mad_i64_i32 v[26:27], s[4:5], v38, s86, v[122:123]
	v_lshl_add_u64 v[26:27], v[26:27], 0, v[124:125]
	v_mul_f32_e32 v28, 0xbfb8aa3b, v22
	v_mul_f32_e32 v29, 0xbfb8aa3b, v24
	v_exp_f32_e32 v28, v28
	v_exp_f32_e32 v29, v29
	s_nop 0
	v_pk_add_f32 v[28:29], v[28:29], 1.0 op_sel_hi:[1,0]
	s_nop 0
	v_rcp_f32_e32 v31, v29
	s_nop 0
	v_fma_f32 v32, -v29, v31, 1.0
	v_fmac_f32_e32 v31, v32, v31
	v_fma_f32 v34, -v29, v31, 1.0
	v_fma_f32 v33, v34, v31, v31
	v_fma_f32 v30, -v29, v33, 1.0
	v_fma_f32 v30, v30, v31, v33
	v_div_fixup_f32 v29, v30, v29, 1.0
	v_rcp_f32_e32 v31, v28
	s_nop 0
	v_fma_f32 v32, -v28, v31, 1.0
	v_fmac_f32_e32 v31, v32, v31
	v_fma_f32 v34, -v28, v31, 1.0
	v_fma_f32 v33, v34, v31, v31
	v_fma_f32 v30, -v28, v33, 1.0
	v_fma_f32 v30, v30, v31, v33
	v_div_fixup_f32 v28, v30, v28, 1.0
	v_mov_b32_e32 v30, v22
	v_mov_b32_e32 v31, v24
	v_pk_mul_f32 v[28:29], v[30:31], v[28:29]
	v_mov_b32_e32 v24, v23
	v_pk_mul_f32 v[22:23], v[24:25], v[28:29]
	v_mul_f32_e32 v24, 0xbfb8aa3b, v18
	v_mul_f32_e32 v25, 0xbfb8aa3b, v20
	v_exp_f32_e32 v24, v24
	v_exp_f32_e32 v25, v25
	s_nop 0
	v_pk_add_f32 v[24:25], v[24:25], 1.0 op_sel_hi:[1,0]
	s_nop 0
	v_rcp_f32_e32 v29, v25
	s_nop 0
	v_fma_f32 v30, -v25, v29, 1.0
	v_fmac_f32_e32 v29, v30, v29
	v_fma_f32 v32, -v25, v29, 1.0
; __device__ __forceinline__ unsigned pkbf(float lo, float hi) { f32x2 v = {lo, hi}; bf16x2v b = __builtin_convertvector(v, bf16x2v); return __builtin_bit_cast(unsigned, b); }
; __device__ __forceinline__ float sigmoidf_(float x) { return 1.f / (1.f + __expf(-x)); }
;     __device__ __forceinline__ void operator()(int row, int col, f32x4 v0, f32x4 v1) const { *(u32x4*)(G + (size_t)row * 1024 + col) = pack8(v0, v1); }
;     __device__ __forceinline__ void operator()(const pg8::f32x4 (&acc)[2][2][4][2], const pg8::Unit& u, int wr, int wc, int fr, int fq) const {
;     ...
;         for (int ai = 0; ai < 2; ++ai)
; #pragma unroll
;             for (int m = 0; m < 4; ++m)
; #pragma unroll
;                 for (int bj = 0; bj < 2; ++bj) { op(row0 + ai * 128 + m * 16, col0 + bj * 128, acc[ai][bj][m][0], acc[ai][bj][m][1]); asm volatile("" ::: "memory"); }
;     __device__ __forceinline__ void operator()(int row, int col, f32x4 v0, f32x4 v1) const {
;         const float h0 = v0.x * sigmoidf_(v0.x) * v0.y, h1 = v0.z * sigmoidf_(v0.z) * v0.w, h2 = v1.x * sigmoidf_(v1.x) * v1.y, h3 = v1.z * sigmoidf_(v1.z) * v1.w;
;         u32x2 o; o.x = pkbf(h0, h1); o.y = pkbf(h2, h3);
;         *(u32x2*)(HID + (size_t)row * DFF + (col >> 1)) = o;
;     }
	v_fma_f32 v31, v32, v29, v29
	v_fma_f32 v28, -v25, v31, 1.0
	v_fma_f32 v28, v28, v29, v31
	v_div_fixup_f32 v25, v28, v25, 1.0
	v_rcp_f32_e32 v29, v24
	s_nop 0
	v_fma_f32 v30, -v24, v29, 1.0
	v_fmac_f32_e32 v29, v30, v29
	v_fma_f32 v32, -v24, v29, 1.0
	v_fma_f32 v31, v32, v29, v29
	v_fma_f32 v28, -v24, v31, 1.0
	v_fma_f32 v28, v28, v29, v31
	v_div_fixup_f32 v24, v28, v24, 1.0
	v_mov_b32_e32 v28, v18
	v_mov_b32_e32 v29, v20
	v_pk_mul_f32 v[24:25], v[28:29], v[24:25]
	v_mov_b32_e32 v20, v19
	v_pk_mul_f32 v[18:19], v[20:21], v[24:25]
	v_cvt_pk_bf16_f32 v202, v22, v23
	v_cvt_pk_bf16_f32 v203, v18, v19
	v_mul_f32_e32 v18, 0xbfb8aa3b, v14
	v_mul_f32_e32 v19, 0xbfb8aa3b, v16
	v_exp_f32_e32 v18, v18
	v_exp_f32_e32 v19, v19
	s_nop 1
	v_permlane16_swap_b32 v200, v202
	v_permlane16_swap_b32 v201, v203
	v_lshl_add_u64 v[204:205], v[26:27], 0, v[206:207]
	global_store_dwordx4 v[204:205], v[200:203], off
	v_add_u32_e32 v22, 0xb0, v144
	v_pk_add_f32 v[18:19], v[18:19], 1.0 op_sel_hi:[1,0]
	s_nop 0
	v_rcp_f32_e32 v21, v19
	s_nop 0
	v_fma_f32 v23, -v19, v21, 1.0
	v_fmac_f32_e32 v21, v23, v21
	v_fma_f32 v25, -v19, v21, 1.0
	v_fma_f32 v24, v25, v21, v21
	v_fma_f32 v20, -v19, v24, 1.0
	v_fma_f32 v20, v20, v21, v24
	v_div_fixup_f32 v19, v20, v19, 1.0
	v_rcp_f32_e32 v21, v18
	s_nop 0
	v_fma_f32 v23, -v18, v21, 1.0
	v_fmac_f32_e32 v21, v23, v21
	v_fma_f32 v25, -v18, v21, 1.0
	v_fma_f32 v24, v25, v21, v21
	v_fma_f32 v20, -v18, v24, 1.0
	v_fma_f32 v20, v20, v21, v24
	v_div_fixup_f32 v18, v20, v18, 1.0
	v_mov_b32_e32 v20, v14
	v_mov_b32_e32 v21, v16
	v_pk_mul_f32 v[18:19], v[20:21], v[18:19]
	v_mov_b32_e32 v16, v15
	v_pk_mul_f32 v[14:15], v[16:17], v[18:19]
	v_mul_f32_e32 v16, 0xbfb8aa3b, v10
	v_mul_f32_e32 v17, 0xbfb8aa3b, v12
	v_exp_f32_e32 v16, v16
	v_exp_f32_e32 v17, v17
	s_nop 0
	v_pk_add_f32 v[16:17], v[16:17], 1.0 op_sel_hi:[1,0]
	s_nop 0
	v_rcp_f32_e32 v19, v17
	s_nop 0
	v_fma_f32 v20, -v17, v19, 1.0
	v_fmac_f32_e32 v19, v20, v19
	v_fma_f32 v23, -v17, v19, 1.0
	v_fma_f32 v21, v23, v19, v19
	v_fma_f32 v18, -v17, v21, 1.0
	v_fma_f32 v18, v18, v19, v21
	v_div_fixup_f32 v17, v18, v17, 1.0
	v_rcp_f32_e32 v19, v16
	s_nop 0
	v_fma_f32 v20, -v16, v19, 1.0
	v_fmac_f32_e32 v19, v20, v19
	v_fma_f32 v23, -v16, v19, 1.0
	v_fma_f32 v21, v23, v19, v19
	v_fma_f32 v18, -v16, v21, 1.0
	v_fma_f32 v18, v18, v19, v21
	v_div_fixup_f32 v16, v18, v16, 1.0
	v_mov_b32_e32 v18, v10
	v_mov_b32_e32 v19, v12
	v_pk_mul_f32 v[16:17], v[18:19], v[16:17]
	v_mov_b32_e32 v12, v11
	v_pk_mul_f32 v[10:11], v[12:13], v[16:17]
	v_cvt_pk_bf16_f32 v200, v14, v15
	v_cvt_pk_bf16_f32 v201, v10, v11
	v_mad_i64_i32 v[10:11], s[4:5], v22, s86, v[122:123]
	v_lshl_add_u64 v[10:11], v[10:11], 0, v[124:125]
	v_mul_f32_e32 v12, 0xbfb8aa3b, v6
	v_mul_f32_e32 v13, 0xbfb8aa3b, v8
	v_exp_f32_e32 v12, v12
	v_exp_f32_e32 v13, v13
	s_nop 0
	v_pk_add_f32 v[12:13], v[12:13], 1.0 op_sel_hi:[1,0]
	s_nop 0
	v_rcp_f32_e32 v15, v13
	s_nop 0
	v_fma_f32 v16, -v13, v15, 1.0
	v_fmac_f32_e32 v15, v16, v15
	v_fma_f32 v18, -v13, v15, 1.0
	v_fma_f32 v17, v18, v15, v15
	v_fma_f32 v14, -v13, v17, 1.0
	v_fma_f32 v14, v14, v15, v17
	v_div_fixup_f32 v13, v14, v13, 1.0
	v_rcp_f32_e32 v15, v12
	s_nop 0
	v_fma_f32 v16, -v12, v15, 1.0
	v_fmac_f32_e32 v15, v16, v15
	v_fma_f32 v18, -v12, v15, 1.0
	v_fma_f32 v17, v18, v15, v15
	v_fma_f32 v14, -v12, v17, 1.0
	v_fma_f32 v14, v14, v15, v17
	v_div_fixup_f32 v12, v14, v12, 1.0
	v_mov_b32_e32 v14, v6
	v_mov_b32_e32 v15, v8
	v_pk_mul_f32 v[12:13], v[14:15], v[12:13]
	v_mov_b32_e32 v8, v7
	v_pk_mul_f32 v[6:7], v[8:9], v[12:13]
	v_mul_f32_e32 v8, 0xbfb8aa3b, v2
	v_mul_f32_e32 v9, 0xbfb8aa3b, v4
	v_exp_f32_e32 v8, v8
	v_exp_f32_e32 v9, v9
	s_nop 0
	v_pk_add_f32 v[8:9], v[8:9], 1.0 op_sel_hi:[1,0]
	s_nop 0
	v_rcp_f32_e32 v13, v9
	s_nop 0
	v_fma_f32 v14, -v9, v13, 1.0
	v_fmac_f32_e32 v13, v14, v13
	v_fma_f32 v16, -v9, v13, 1.0
	v_fma_f32 v15, v16, v13, v13
	v_fma_f32 v12, -v9, v15, 1.0
	v_fma_f32 v12, v12, v13, v15
	v_div_fixup_f32 v9, v12, v9, 1.0
	v_rcp_f32_e32 v13, v8
	s_mov_b64 s[4:5], -1
	v_fma_f32 v14, -v8, v13, 1.0
	v_fmac_f32_e32 v13, v14, v13
	v_fma_f32 v16, -v8, v13, 1.0
	v_fma_f32 v15, v16, v13, v13
	v_fma_f32 v12, -v8, v15, 1.0
	v_fma_f32 v12, v12, v13, v15
	v_div_fixup_f32 v8, v12, v8, 1.0
	v_mov_b32_e32 v12, v2
	v_mov_b32_e32 v13, v4
	v_pk_mul_f32 v[8:9], v[12:13], v[8:9]
	v_mov_b32_e32 v4, v3
	v_pk_mul_f32 v[2:3], v[4:5], v[8:9]
	v_cvt_pk_bf16_f32 v202, v6, v7
	v_cvt_pk_bf16_f32 v203, v2, v3
	s_nop 1
	v_permlane16_swap_b32 v200, v202
	v_permlane16_swap_b32 v201, v203
	v_lshl_add_u64 v[204:205], v[10:11], 0, v[206:207]
	global_store_dwordx4 v[204:205], v[200:203], off
	s_and_b64 vcc, exec, s[40:41]
	s_cbranch_vccnz .LBB0_25
	s_andn2_b64 vcc, exec, s[50:51]
	s_cbranch_vccnz .LBB0_24
	s_barrier
	s_branch .LBB0_24
